# S7 output stores without nt hint (let L2/MALL absorb the write burst)
# speedup vs baseline: 1.0050x; 1.0050x over previous
.LBB0_1487:
	v_lshl_add_u32 v148, s35, 8, v152
	v_lshl_add_u32 v144, s36, 8, v154
	v_ashrrev_i32_e32 v145, 31, v144
	v_ashrrev_i32_e32 v149, 31, v148
	v_lshl_add_u64 v[146:147], v[144:145], 1, s[8:9]
	v_lshlrev_b64 v[150:151], 12, v[148:149]
	v_or_b32_e32 v182, 16, v148
	v_lshl_add_u64 v[150:151], v[146:147], 0, v[150:151]
	v_ashrrev_i32_e32 v183, 31, v182
	flat_load_dwordx4 v[158:161], v[150:151]
	flat_load_dwordx4 v[162:165], v[150:151] offset:256
	v_lshlrev_b64 v[150:151], 12, v[182:183]
	v_or_b32_e32 v190, 32, v148
	v_lshl_add_u64 v[150:151], v[146:147], 0, v[150:151]
	v_ashrrev_i32_e32 v191, 31, v190
	flat_load_dwordx4 v[166:169], v[150:151]
	flat_load_dwordx4 v[170:173], v[150:151] offset:256
	v_lshlrev_b64 v[150:151], 12, v[190:191]
	v_lshl_add_u64 v[178:179], v[146:147], 0, v[150:151]
	flat_load_dwordx4 v[174:177], v[178:179]
	v_or_b32_e32 v150, 48, v148
	flat_load_dwordx4 v[178:181], v[178:179] offset:256
	v_ashrrev_i32_e32 v151, 31, v150
	v_lshlrev_b64 v[186:187], 12, v[150:151]
	v_lshl_add_u64 v[144:145], v[144:145], 2, s[52:53]
	v_lshlrev_b64 v[184:185], 13, v[148:149]
	v_lshlrev_b64 v[182:183], 13, v[182:183]
	v_lshl_add_u64 v[186:187], v[146:147], 0, v[186:187]
	v_lshl_add_u64 v[192:193], v[144:145], 0, v[184:185]
	v_lshl_add_u64 v[194:195], v[144:145], 0, v[182:183]
	flat_load_dwordx4 v[182:185], v[186:187]
	s_nop 0
	flat_load_dwordx4 v[186:189], v[186:187] offset:256
	s_and_b64 vcc, exec, s[6:7]
	s_mov_b64 s[6:7], -1
	s_waitcnt vmcnt(0) lgkmcnt(0)
	v_lshlrev_b32_e32 v196, 16, v158
	v_and_b32_e32 v197, 0xffff0000, v158
	v_lshlrev_b32_e32 v158, 16, v159
	v_and_b32_e32 v159, 0xffff0000, v159
	v_lshlrev_b32_e32 v198, 16, v160
	v_and_b32_e32 v199, 0xffff0000, v160
	v_lshlrev_b32_e32 v160, 16, v161
	v_and_b32_e32 v161, 0xffff0000, v161
	v_lshlrev_b32_e32 v200, 16, v162
	v_and_b32_e32 v201, 0xffff0000, v162
	v_lshlrev_b32_e32 v162, 16, v163
	v_and_b32_e32 v163, 0xffff0000, v163
	v_lshlrev_b32_e32 v202, 16, v164
	v_and_b32_e32 v203, 0xffff0000, v164
	v_lshlrev_b32_e32 v164, 16, v165
	v_and_b32_e32 v165, 0xffff0000, v165
	v_pk_fma_f32 v[126:127], v[126:127], 0.5, v[158:159] op_sel_hi:[1,0,1]
	v_pk_fma_f32 v[122:123], v[122:123], 0.5, v[160:161] op_sel_hi:[1,0,1]
	v_pk_fma_f32 v[118:119], v[118:119], 0.5, v[162:163] op_sel_hi:[1,0,1]
	v_pk_fma_f32 v[114:115], v[114:115], 0.5, v[164:165] op_sel_hi:[1,0,1]
	v_lshlrev_b32_e32 v158, 16, v166
	v_and_b32_e32 v159, 0xffff0000, v166
	v_lshlrev_b32_e32 v160, 16, v167
	v_and_b32_e32 v161, 0xffff0000, v167
	v_lshlrev_b32_e32 v162, 16, v168
	v_and_b32_e32 v163, 0xffff0000, v168
	v_lshlrev_b32_e32 v164, 16, v169
	v_and_b32_e32 v165, 0xffff0000, v169
	v_lshlrev_b32_e32 v166, 16, v170
	v_and_b32_e32 v167, 0xffff0000, v170
	v_lshlrev_b32_e32 v168, 16, v171
	v_and_b32_e32 v169, 0xffff0000, v171
	v_lshlrev_b32_e32 v170, 16, v172
	v_and_b32_e32 v171, 0xffff0000, v172
	v_lshlrev_b32_e32 v172, 16, v173
	v_and_b32_e32 v173, 0xffff0000, v173
	v_pk_fma_f32 v[124:125], v[124:125], 0.5, v[196:197] op_sel_hi:[1,0,1]
	v_pk_fma_f32 v[110:111], v[110:111], 0.5, v[160:161] op_sel_hi:[1,0,1]
	v_pk_fma_f32 v[108:109], v[108:109], 0.5, v[158:159] op_sel_hi:[1,0,1]
	v_pk_fma_f32 v[104:105], v[104:105], 0.5, v[162:163] op_sel_hi:[1,0,1]
	v_pk_fma_f32 v[102:103], v[102:103], 0.5, v[168:169] op_sel_hi:[1,0,1]
	v_pk_fma_f32 v[100:101], v[100:101], 0.5, v[166:167] op_sel_hi:[1,0,1]
	v_pk_fma_f32 v[98:99], v[98:99], 0.5, v[172:173] op_sel_hi:[1,0,1]
	v_pk_fma_f32 v[96:97], v[96:97], 0.5, v[170:171] op_sel_hi:[1,0,1]
	v_pk_fma_f32 v[120:121], v[120:121], 0.5, v[198:199] op_sel_hi:[1,0,1]
	v_pk_fma_f32 v[116:117], v[116:117], 0.5, v[200:201] op_sel_hi:[1,0,1]
	v_pk_fma_f32 v[112:113], v[112:113], 0.5, v[202:203] op_sel_hi:[1,0,1]
	global_store_dwordx4 v[192:193], v[124:127], off
	global_store_dwordx4 v[192:193], v[120:123], off offset:16
	global_store_dwordx4 v[192:193], v[116:119], off offset:512
	global_store_dwordx4 v[192:193], v[112:115], off offset:528
	v_pk_fma_f32 v[106:107], v[106:107], 0.5, v[164:165] op_sel_hi:[1,0,1]
	global_store_dwordx4 v[194:195], v[108:111], off
	global_store_dwordx4 v[194:195], v[104:107], off offset:16
	global_store_dwordx4 v[194:195], v[100:103], off offset:512
	global_store_dwordx4 v[194:195], v[96:99], off offset:528
	v_lshlrev_b32_e32 v104, 16, v177
	v_lshlrev_b32_e32 v100, 16, v175
	v_lshlrev_b64 v[96:97], 13, v[190:191]
	v_lshlrev_b32_e32 v98, 16, v174
	v_and_b32_e32 v99, 0xffff0000, v174
	v_and_b32_e32 v101, 0xffff0000, v175
	v_lshlrev_b32_e32 v102, 16, v176
	v_and_b32_e32 v103, 0xffff0000, v176
	v_and_b32_e32 v105, 0xffff0000, v177
	v_lshl_add_u64 v[96:97], v[144:145], 0, v[96:97]
	v_pk_fma_f32 v[94:95], v[94:95], 0.5, v[100:101] op_sel_hi:[1,0,1]
	v_pk_fma_f32 v[92:93], v[92:93], 0.5, v[98:99] op_sel_hi:[1,0,1]
	v_pk_fma_f32 v[90:91], v[90:91], 0.5, v[104:105] op_sel_hi:[1,0,1]
	v_pk_fma_f32 v[88:89], v[88:89], 0.5, v[102:103] op_sel_hi:[1,0,1]
	global_store_dwordx4 v[96:97], v[92:95], off
	global_store_dwordx4 v[96:97], v[88:91], off offset:16
	v_add_u32_e32 v98, 0x90, v148
	v_lshlrev_b32_e32 v92, 16, v180
	v_lshlrev_b32_e32 v88, 16, v178
	v_and_b32_e32 v89, 0xffff0000, v178
	v_lshlrev_b32_e32 v90, 16, v179
	v_and_b32_e32 v91, 0xffff0000, v179
	v_and_b32_e32 v93, 0xffff0000, v180
	v_lshlrev_b32_e32 v94, 16, v181
	v_and_b32_e32 v95, 0xffff0000, v181
	v_pk_fma_f32 v[86:87], v[86:87], 0.5, v[90:91] op_sel_hi:[1,0,1]
	v_pk_fma_f32 v[84:85], v[84:85], 0.5, v[88:89] op_sel_hi:[1,0,1]
	v_pk_fma_f32 v[76:77], v[76:77], 0.5, v[92:93] op_sel_hi:[1,0,1]
	v_pk_fma_f32 v[78:79], v[78:79], 0.5, v[94:95] op_sel_hi:[1,0,1]
	global_store_dwordx4 v[96:97], v[84:87], off offset:512
	global_store_dwordx4 v[96:97], v[76:79], off offset:528
	v_lshlrev_b32_e32 v88, 16, v185
	v_lshlrev_b32_e32 v86, 16, v184
	v_lshlrev_b64 v[76:77], 13, v[150:151]
	v_lshl_add_u64 v[84:85], v[144:145], 0, v[76:77]
	v_lshlrev_b32_e32 v76, 16, v182
	v_and_b32_e32 v77, 0xffff0000, v182
	v_lshlrev_b32_e32 v78, 16, v183
	v_and_b32_e32 v79, 0xffff0000, v183
	v_and_b32_e32 v87, 0xffff0000, v184
	v_and_b32_e32 v89, 0xffff0000, v185
	v_pk_fma_f32 v[78:79], v[82:83], 0.5, v[78:79] op_sel_hi:[1,0,1]
	v_pk_fma_f32 v[76:77], v[80:81], 0.5, v[76:77] op_sel_hi:[1,0,1]
	v_pk_fma_f32 v[74:75], v[74:75], 0.5, v[88:89] op_sel_hi:[1,0,1]
	v_pk_fma_f32 v[72:73], v[72:73], 0.5, v[86:87] op_sel_hi:[1,0,1]
	global_store_dwordx4 v[84:85], v[76:79], off
	global_store_dwordx4 v[84:85], v[72:75], off offset:16
	v_add_u32_e32 v96, 0x80, v148
	v_lshlrev_b32_e32 v76, 16, v188
	v_lshlrev_b32_e32 v72, 16, v186
	v_and_b32_e32 v73, 0xffff0000, v186
	v_lshlrev_b32_e32 v74, 16, v187
	v_and_b32_e32 v75, 0xffff0000, v187
	v_and_b32_e32 v77, 0xffff0000, v188
	v_lshlrev_b32_e32 v78, 16, v189
	v_and_b32_e32 v79, 0xffff0000, v189
	v_pk_fma_f32 v[70:71], v[70:71], 0.5, v[74:75] op_sel_hi:[1,0,1]
	v_pk_fma_f32 v[68:69], v[68:69], 0.5, v[72:73] op_sel_hi:[1,0,1]
	v_pk_fma_f32 v[64:65], v[64:65], 0.5, v[76:77] op_sel_hi:[1,0,1]
	v_ashrrev_i32_e32 v97, 31, v96
	v_pk_fma_f32 v[66:67], v[66:67], 0.5, v[78:79] op_sel_hi:[1,0,1]
	global_store_dwordx4 v[84:85], v[68:71], off offset:512
	global_store_dwordx4 v[84:85], v[64:67], off offset:528
	v_ashrrev_i32_e32 v99, 31, v98
	v_add_u32_e32 v100, 0xa0, v148
	v_lshlrev_b64 v[64:65], 12, v[96:97]
	v_lshl_add_u64 v[64:65], v[146:147], 0, v[64:65]
	flat_load_dwordx4 v[68:71], v[64:65]
	flat_load_dwordx4 v[72:75], v[64:65] offset:256
	v_lshlrev_b64 v[64:65], 12, v[98:99]
	v_lshl_add_u64 v[64:65], v[146:147], 0, v[64:65]
	flat_load_dwordx4 v[76:79], v[64:65]
	flat_load_dwordx4 v[80:83], v[64:65] offset:256
	v_ashrrev_i32_e32 v101, 31, v100
	v_lshlrev_b64 v[64:65], 12, v[100:101]
	v_lshl_add_u64 v[64:65], v[146:147], 0, v[64:65]
	flat_load_dwordx4 v[84:87], v[64:65]
	flat_load_dwordx4 v[88:91], v[64:65] offset:256
	v_add_u32_e32 v102, 0xb0, v148
	v_ashrrev_i32_e32 v103, 31, v102
	v_lshlrev_b64 v[64:65], 12, v[102:103]
	v_lshl_add_u64 v[64:65], v[146:147], 0, v[64:65]
	flat_load_dwordx4 v[92:95], v[64:65]
	s_nop 0
	flat_load_dwordx4 v[64:67], v[64:65] offset:256
	v_lshlrev_b64 v[96:97], 13, v[96:97]
	v_lshl_add_u64 v[96:97], v[144:145], 0, v[96:97]
	s_waitcnt vmcnt(0) lgkmcnt(0)
	v_lshlrev_b32_e32 v104, 16, v68
	v_and_b32_e32 v105, 0xffff0000, v68
	v_lshlrev_b32_e32 v68, 16, v69
	v_and_b32_e32 v69, 0xffff0000, v69
	v_lshlrev_b32_e32 v106, 16, v70
	v_and_b32_e32 v107, 0xffff0000, v70
	v_lshlrev_b32_e32 v70, 16, v71
	v_and_b32_e32 v71, 0xffff0000, v71
	v_pk_fma_f32 v[62:63], v[62:63], 0.5, v[68:69] op_sel_hi:[1,0,1]
	v_pk_fma_f32 v[60:61], v[60:61], 0.5, v[104:105] op_sel_hi:[1,0,1]
	v_pk_fma_f32 v[58:59], v[58:59], 0.5, v[70:71] op_sel_hi:[1,0,1]
	v_pk_fma_f32 v[56:57], v[56:57], 0.5, v[106:107] op_sel_hi:[1,0,1]
	global_store_dwordx4 v[96:97], v[60:63], off
	global_store_dwordx4 v[96:97], v[56:59], off offset:16
	s_nop 0
	v_lshlrev_b32_e32 v60, 16, v74
	v_lshlrev_b32_e32 v56, 16, v72
	v_and_b32_e32 v57, 0xffff0000, v72
	v_lshlrev_b32_e32 v58, 16, v73
	v_and_b32_e32 v59, 0xffff0000, v73
	v_and_b32_e32 v61, 0xffff0000, v74
	v_lshlrev_b32_e32 v62, 16, v75
	v_and_b32_e32 v63, 0xffff0000, v75
	v_pk_fma_f32 v[54:55], v[54:55], 0.5, v[58:59] op_sel_hi:[1,0,1]
	v_pk_fma_f32 v[52:53], v[52:53], 0.5, v[56:57] op_sel_hi:[1,0,1]
	v_pk_fma_f32 v[44:45], v[44:45], 0.5, v[60:61] op_sel_hi:[1,0,1]
	v_pk_fma_f32 v[46:47], v[46:47], 0.5, v[62:63] op_sel_hi:[1,0,1]
	global_store_dwordx4 v[96:97], v[52:55], off offset:512
	global_store_dwordx4 v[96:97], v[44:47], off offset:528
	v_lshlrev_b32_e32 v56, 16, v79
	v_lshlrev_b32_e32 v54, 16, v78
	v_lshlrev_b64 v[44:45], 13, v[98:99]
	v_lshl_add_u64 v[52:53], v[144:145], 0, v[44:45]
	v_lshlrev_b32_e32 v44, 16, v76
	v_and_b32_e32 v45, 0xffff0000, v76
	v_lshlrev_b32_e32 v46, 16, v77
	v_and_b32_e32 v47, 0xffff0000, v77
	v_and_b32_e32 v55, 0xffff0000, v78
	v_and_b32_e32 v57, 0xffff0000, v79
	v_pk_fma_f32 v[46:47], v[50:51], 0.5, v[46:47] op_sel_hi:[1,0,1]
	v_pk_fma_f32 v[44:45], v[48:49], 0.5, v[44:45] op_sel_hi:[1,0,1]
	v_pk_fma_f32 v[42:43], v[42:43], 0.5, v[56:57] op_sel_hi:[1,0,1]
	v_pk_fma_f32 v[40:41], v[40:41], 0.5, v[54:55] op_sel_hi:[1,0,1]
	global_store_dwordx4 v[52:53], v[44:47], off
	global_store_dwordx4 v[52:53], v[40:43], off offset:16
	s_nop 0
	v_lshlrev_b32_e32 v44, 16, v82
	v_lshlrev_b32_e32 v40, 16, v80
	v_and_b32_e32 v41, 0xffff0000, v80
	v_lshlrev_b32_e32 v42, 16, v81
	v_and_b32_e32 v43, 0xffff0000, v81
	v_and_b32_e32 v45, 0xffff0000, v82
	v_lshlrev_b32_e32 v46, 16, v83
	v_and_b32_e32 v47, 0xffff0000, v83
	v_pk_fma_f32 v[38:39], v[38:39], 0.5, v[42:43] op_sel_hi:[1,0,1]
	v_pk_fma_f32 v[36:37], v[36:37], 0.5, v[40:41] op_sel_hi:[1,0,1]
	v_pk_fma_f32 v[28:29], v[28:29], 0.5, v[44:45] op_sel_hi:[1,0,1]
	v_pk_fma_f32 v[30:31], v[30:31], 0.5, v[46:47] op_sel_hi:[1,0,1]
	global_store_dwordx4 v[52:53], v[36:39], off offset:512
	global_store_dwordx4 v[52:53], v[28:31], off offset:528
	v_lshlrev_b32_e32 v40, 16, v87
	v_lshlrev_b32_e32 v38, 16, v86
	v_lshlrev_b64 v[28:29], 13, v[100:101]
	v_lshl_add_u64 v[36:37], v[144:145], 0, v[28:29]
	v_lshlrev_b32_e32 v28, 16, v84
	v_and_b32_e32 v29, 0xffff0000, v84
	v_lshlrev_b32_e32 v30, 16, v85
	v_and_b32_e32 v31, 0xffff0000, v85
	v_and_b32_e32 v39, 0xffff0000, v86
	v_and_b32_e32 v41, 0xffff0000, v87
	v_pk_fma_f32 v[30:31], v[34:35], 0.5, v[30:31] op_sel_hi:[1,0,1]
	v_pk_fma_f32 v[28:29], v[32:33], 0.5, v[28:29] op_sel_hi:[1,0,1]
	v_pk_fma_f32 v[26:27], v[26:27], 0.5, v[40:41] op_sel_hi:[1,0,1]
	v_pk_fma_f32 v[24:25], v[24:25], 0.5, v[38:39] op_sel_hi:[1,0,1]
	global_store_dwordx4 v[36:37], v[28:31], off
	global_store_dwordx4 v[36:37], v[24:27], off offset:16
	s_nop 0
	v_lshlrev_b32_e32 v28, 16, v90
	v_lshlrev_b32_e32 v24, 16, v88
	v_and_b32_e32 v25, 0xffff0000, v88
	v_lshlrev_b32_e32 v26, 16, v89
	v_and_b32_e32 v27, 0xffff0000, v89
	v_and_b32_e32 v29, 0xffff0000, v90
	v_lshlrev_b32_e32 v30, 16, v91
	v_and_b32_e32 v31, 0xffff0000, v91
	v_pk_fma_f32 v[22:23], v[22:23], 0.5, v[26:27] op_sel_hi:[1,0,1]
	v_pk_fma_f32 v[20:21], v[20:21], 0.5, v[24:25] op_sel_hi:[1,0,1]
	v_pk_fma_f32 v[12:13], v[12:13], 0.5, v[28:29] op_sel_hi:[1,0,1]
	v_pk_fma_f32 v[14:15], v[14:15], 0.5, v[30:31] op_sel_hi:[1,0,1]
	global_store_dwordx4 v[36:37], v[20:23], off offset:512
	global_store_dwordx4 v[36:37], v[12:15], off offset:528
	v_lshlrev_b32_e32 v24, 16, v95
	v_lshlrev_b32_e32 v22, 16, v94
	v_lshlrev_b64 v[12:13], 13, v[102:103]
	v_lshl_add_u64 v[20:21], v[144:145], 0, v[12:13]
	v_lshlrev_b32_e32 v12, 16, v92
	v_and_b32_e32 v13, 0xffff0000, v92
	v_lshlrev_b32_e32 v14, 16, v93
	v_and_b32_e32 v15, 0xffff0000, v93
	v_and_b32_e32 v23, 0xffff0000, v94
	v_and_b32_e32 v25, 0xffff0000, v95
	v_pk_fma_f32 v[14:15], v[18:19], 0.5, v[14:15] op_sel_hi:[1,0,1]
	v_pk_fma_f32 v[12:13], v[16:17], 0.5, v[12:13] op_sel_hi:[1,0,1]
	v_pk_fma_f32 v[10:11], v[10:11], 0.5, v[24:25] op_sel_hi:[1,0,1]
	v_pk_fma_f32 v[8:9], v[8:9], 0.5, v[22:23] op_sel_hi:[1,0,1]
	global_store_dwordx4 v[20:21], v[12:15], off
	global_store_dwordx4 v[20:21], v[8:11], off offset:16
	s_nop 0
	v_lshlrev_b32_e32 v12, 16, v66
	v_lshlrev_b32_e32 v8, 16, v64
	v_and_b32_e32 v9, 0xffff0000, v64
	v_lshlrev_b32_e32 v10, 16, v65
	v_and_b32_e32 v11, 0xffff0000, v65
	v_and_b32_e32 v13, 0xffff0000, v66
	v_lshlrev_b32_e32 v14, 16, v67
	v_and_b32_e32 v15, 0xffff0000, v67
	v_pk_fma_f32 v[6:7], v[6:7], 0.5, v[10:11] op_sel_hi:[1,0,1]
	v_pk_fma_f32 v[4:5], v[4:5], 0.5, v[8:9] op_sel_hi:[1,0,1]
	v_pk_fma_f32 v[2:3], v[2:3], 0.5, v[14:15] op_sel_hi:[1,0,1]
	v_pk_fma_f32 v[0:1], v[0:1], 0.5, v[12:13] op_sel_hi:[1,0,1]
	global_store_dwordx4 v[20:21], v[4:7], off offset:512
	global_store_dwordx4 v[20:21], v[0:3], off offset:528
	s_cbranch_vccnz .LBB0_1472
	s_and_b64 vcc, exec, s[60:61]
	s_cbranch_vccnz .LBB0_1471
	s_barrier
	s_branch .LBB0_1471
